# ssm1 U-block gather via direct HBM->LDS loads (global_load_lds_dwordx4) instead of VGPR staging + ds_write
# baseline (speedup 1.0000x reference)
.LBB0_303:
	v_lshrrev_b32_e32 v18, 6, v188
	v_lshl_add_u64 v[134:135], s[94:95], 0, v[14:15]
	v_readfirstlane_b32 s0, v18
	v_add_co_u32_e32 v134, vcc, 0x6c00200, v134
	s_nop 1
	v_addc_co_u32_e32 v135, vcc, 0, v135, vcc
	s_mul_i32 s0, s0, 0xa000
	s_mov_b32 s1, 0
	s_mov_b64 s[98:99], 0x1400
	v_lshl_add_u64 v[134:135], v[134:135], 0, s[0:1]
	v_readfirstlane_b32 s1, v18
	s_lshl_b32 s1, s1, 13
	s_mov_b32 m0, s1
	s_nop 0
	global_load_lds_dwordx4 v[134:135], off
	s_add_u32 m0, m0, 0x400
	v_lshl_add_u64 v[134:135], v[134:135], 0, s[98:99]
	global_load_lds_dwordx4 v[134:135], off
	s_add_u32 m0, m0, 0x400
	v_lshl_add_u64 v[134:135], v[134:135], 0, s[98:99]
	global_load_lds_dwordx4 v[134:135], off
	s_add_u32 m0, m0, 0x400
	v_lshl_add_u64 v[134:135], v[134:135], 0, s[98:99]
	global_load_lds_dwordx4 v[134:135], off
	s_add_u32 m0, m0, 0x400
	v_lshl_add_u64 v[134:135], v[134:135], 0, s[98:99]
	global_load_lds_dwordx4 v[134:135], off
	s_add_u32 m0, m0, 0x400
	v_lshl_add_u64 v[134:135], v[134:135], 0, s[98:99]
	global_load_lds_dwordx4 v[134:135], off
	s_add_u32 m0, m0, 0x400
	v_lshl_add_u64 v[134:135], v[134:135], 0, s[98:99]
	global_load_lds_dwordx4 v[134:135], off
	s_add_u32 m0, m0, 0x400
	v_lshl_add_u64 v[134:135], v[134:135], 0, s[98:99]
	global_load_lds_dwordx4 v[134:135], off
	v_lshl_add_u64 v[22:23], s[94:95], 0, v[16:17]
	v_add_co_u32_e32 v18, vcc, 0x13a58000, v22
	s_nop 1
	v_addc_co_u32_e32 v19, vcc, 0, v23, vcc
	v_add_co_u32_e32 v22, vcc, 0x13a60000, v22
	s_nop 1
	v_addc_co_u32_e32 v23, vcc, 0, v23, vcc
	v_and_b32_e32 v136, 63, v188
	v_lshlrev_b32_e32 v136, 4, v136
	v_lshrrev_b32_e32 v137, 6, v188
	v_lshl_add_u32 v137, v137, 13, v136
	global_load_dwordx4 v[70:73], v[18:19], off offset:0
	global_load_dwordx4 v[102:105], v[22:23], off offset:0
	global_load_dwordx4 v[74:77], v[18:19], off offset:64
	global_load_dwordx4 v[106:109], v[22:23], off offset:64
	global_load_dwordx4 v[78:81], v[18:19], off offset:128
	global_load_dwordx4 v[110:113], v[22:23], off offset:128
	global_load_dwordx4 v[82:85], v[18:19], off offset:192
	global_load_dwordx4 v[114:117], v[22:23], off offset:192
	global_load_dwordx4 v[86:89], v[18:19], off offset:256
	global_load_dwordx4 v[118:121], v[22:23], off offset:256
	global_load_dwordx4 v[90:93], v[18:19], off offset:320
	global_load_dwordx4 v[122:125], v[22:23], off offset:320
	global_load_dwordx4 v[94:97], v[18:19], off offset:384
	global_load_dwordx4 v[126:129], v[22:23], off offset:384
	global_load_dwordx4 v[98:101], v[18:19], off offset:448
	global_load_dwordx4 v[130:133], v[22:23], off offset:448
	s_waitcnt vmcnt(16)
	s_waitcnt lgkmcnt(0)
	s_barrier
	ds_read_b128 v[138:141], v136 offset:0
	ds_read_b128 v[142:145], v136 offset:1024
	ds_read_b128 v[146:149], v136 offset:2048
	ds_read_b128 v[150:153], v136 offset:3072
	ds_read_b128 v[154:157], v136 offset:4096
	ds_read_b128 v[158:161], v136 offset:5120
	ds_read_b128 v[162:165], v136 offset:6144
	ds_read_b128 v[166:169], v136 offset:7168
	global_load_dwordx4 v[38:41], v[18:19], off offset:512
	global_load_dwordx4 v[214:217], v[22:23], off offset:512
	global_load_dwordx4 v[42:45], v[18:19], off offset:576
	global_load_dwordx4 v[218:221], v[22:23], off offset:576
	global_load_dwordx4 v[46:49], v[18:19], off offset:640
	global_load_dwordx4 v[222:225], v[22:23], off offset:640
	global_load_dwordx4 v[50:53], v[18:19], off offset:704
	global_load_dwordx4 v[226:229], v[22:23], off offset:704
	global_load_dwordx4 v[54:57], v[18:19], off offset:768
	global_load_dwordx4 v[230:233], v[22:23], off offset:768
	global_load_dwordx4 v[58:61], v[18:19], off offset:832
	global_load_dwordx4 v[234:237], v[22:23], off offset:832
	global_load_dwordx4 v[62:65], v[18:19], off offset:896
	global_load_dwordx4 v[238:241], v[22:23], off offset:896
	global_load_dwordx4 v[66:69], v[18:19], off offset:960
	global_load_dwordx4 v[242:245], v[22:23], off offset:960
	s_waitcnt vmcnt(30) lgkmcnt(7)
	v_mfma_f32_16x16x32_bf16 v[2:5], v[70:73], v[138:141], v[2:5]
	v_mfma_f32_16x16x32_bf16 v[6:9], v[102:105], v[138:141], v[6:9]
	s_waitcnt vmcnt(28) lgkmcnt(6)
	v_mfma_f32_16x16x32_bf16 v[2:5], v[74:77], v[142:145], v[2:5]
	v_mfma_f32_16x16x32_bf16 v[6:9], v[106:109], v[142:145], v[6:9]
	s_waitcnt vmcnt(26) lgkmcnt(5)
	v_mfma_f32_16x16x32_bf16 v[2:5], v[78:81], v[146:149], v[2:5]
	v_mfma_f32_16x16x32_bf16 v[6:9], v[110:113], v[146:149], v[6:9]
	s_waitcnt vmcnt(24) lgkmcnt(4)
	v_mfma_f32_16x16x32_bf16 v[2:5], v[82:85], v[150:153], v[2:5]
	v_mfma_f32_16x16x32_bf16 v[6:9], v[114:117], v[150:153], v[6:9]
	s_waitcnt vmcnt(22) lgkmcnt(3)
	v_mfma_f32_16x16x32_bf16 v[2:5], v[86:89], v[154:157], v[2:5]
	v_mfma_f32_16x16x32_bf16 v[6:9], v[118:121], v[154:157], v[6:9]
	s_waitcnt vmcnt(20) lgkmcnt(2)
	v_mfma_f32_16x16x32_bf16 v[2:5], v[90:93], v[158:161], v[2:5]
	v_mfma_f32_16x16x32_bf16 v[6:9], v[122:125], v[158:161], v[6:9]
	s_waitcnt vmcnt(18) lgkmcnt(1)
	v_mfma_f32_16x16x32_bf16 v[2:5], v[94:97], v[162:165], v[2:5]
	v_mfma_f32_16x16x32_bf16 v[6:9], v[126:129], v[162:165], v[6:9]
	s_waitcnt vmcnt(16) lgkmcnt(0)
	v_mfma_f32_16x16x32_bf16 v[2:5], v[98:101], v[166:169], v[2:5]
	v_mfma_f32_16x16x32_bf16 v[6:9], v[130:133], v[166:169], v[6:9]
	ds_read_b128 v[138:141], v136 offset:8192
	ds_read_b128 v[142:145], v136 offset:9216
	ds_read_b128 v[146:149], v136 offset:10240
	ds_read_b128 v[150:153], v136 offset:11264
	ds_read_b128 v[154:157], v136 offset:12288
	ds_read_b128 v[158:161], v136 offset:13312
	ds_read_b128 v[162:165], v136 offset:14336
	ds_read_b128 v[166:169], v136 offset:15360
	global_load_dwordx4 v[70:73], v[18:19], off offset:1024
	global_load_dwordx4 v[102:105], v[22:23], off offset:1024
	global_load_dwordx4 v[74:77], v[18:19], off offset:1088
	global_load_dwordx4 v[106:109], v[22:23], off offset:1088
	global_load_dwordx4 v[78:81], v[18:19], off offset:1152
	global_load_dwordx4 v[110:113], v[22:23], off offset:1152
	global_load_dwordx4 v[82:85], v[18:19], off offset:1216
	global_load_dwordx4 v[114:117], v[22:23], off offset:1216
	global_load_dwordx4 v[86:89], v[18:19], off offset:1280
	global_load_dwordx4 v[118:121], v[22:23], off offset:1280
	global_load_dwordx4 v[90:93], v[18:19], off offset:1344
	global_load_dwordx4 v[122:125], v[22:23], off offset:1344
	global_load_dwordx4 v[94:97], v[18:19], off offset:1408
	global_load_dwordx4 v[126:129], v[22:23], off offset:1408
	global_load_dwordx4 v[98:101], v[18:19], off offset:1472
	global_load_dwordx4 v[130:133], v[22:23], off offset:1472
	s_waitcnt vmcnt(30) lgkmcnt(7)
	v_mfma_f32_16x16x32_bf16 v[2:5], v[38:41], v[138:141], v[2:5]
	v_mfma_f32_16x16x32_bf16 v[6:9], v[214:217], v[138:141], v[6:9]
	s_waitcnt vmcnt(28) lgkmcnt(6)
	v_mfma_f32_16x16x32_bf16 v[2:5], v[42:45], v[142:145], v[2:5]
	v_mfma_f32_16x16x32_bf16 v[6:9], v[218:221], v[142:145], v[6:9]
	s_waitcnt vmcnt(26) lgkmcnt(5)
	v_mfma_f32_16x16x32_bf16 v[2:5], v[46:49], v[146:149], v[2:5]
	v_mfma_f32_16x16x32_bf16 v[6:9], v[222:225], v[146:149], v[6:9]
	s_waitcnt vmcnt(24) lgkmcnt(4)
	v_mfma_f32_16x16x32_bf16 v[2:5], v[50:53], v[150:153], v[2:5]
	v_mfma_f32_16x16x32_bf16 v[6:9], v[226:229], v[150:153], v[6:9]
	s_waitcnt vmcnt(22) lgkmcnt(3)
	v_mfma_f32_16x16x32_bf16 v[2:5], v[54:57], v[154:157], v[2:5]
	v_mfma_f32_16x16x32_bf16 v[6:9], v[230:233], v[154:157], v[6:9]
	s_waitcnt vmcnt(20) lgkmcnt(2)
	v_mfma_f32_16x16x32_bf16 v[2:5], v[58:61], v[158:161], v[2:5]
	v_mfma_f32_16x16x32_bf16 v[6:9], v[234:237], v[158:161], v[6:9]
	s_waitcnt vmcnt(18) lgkmcnt(1)
	v_mfma_f32_16x16x32_bf16 v[2:5], v[62:65], v[162:165], v[2:5]
	v_mfma_f32_16x16x32_bf16 v[6:9], v[238:241], v[162:165], v[6:9]
	s_waitcnt vmcnt(16) lgkmcnt(0)
	v_mfma_f32_16x16x32_bf16 v[2:5], v[66:69], v[166:169], v[2:5]
	v_mfma_f32_16x16x32_bf16 v[6:9], v[242:245], v[166:169], v[6:9]
	ds_read_b128 v[138:141], v136 offset:16384
	ds_read_b128 v[142:145], v136 offset:17408
	ds_read_b128 v[146:149], v136 offset:18432
	ds_read_b128 v[150:153], v136 offset:19456
	ds_read_b128 v[154:157], v136 offset:20480
	ds_read_b128 v[158:161], v136 offset:21504
	ds_read_b128 v[162:165], v136 offset:22528
	ds_read_b128 v[166:169], v136 offset:23552
	global_load_dwordx4 v[38:41], v[18:19], off offset:1536
	global_load_dwordx4 v[214:217], v[22:23], off offset:1536
	global_load_dwordx4 v[42:45], v[18:19], off offset:1600
	global_load_dwordx4 v[218:221], v[22:23], off offset:1600
	global_load_dwordx4 v[46:49], v[18:19], off offset:1664
	global_load_dwordx4 v[222:225], v[22:23], off offset:1664
	global_load_dwordx4 v[50:53], v[18:19], off offset:1728
	global_load_dwordx4 v[226:229], v[22:23], off offset:1728
	global_load_dwordx4 v[54:57], v[18:19], off offset:1792
	global_load_dwordx4 v[230:233], v[22:23], off offset:1792
	global_load_dwordx4 v[58:61], v[18:19], off offset:1856
	global_load_dwordx4 v[234:237], v[22:23], off offset:1856
	global_load_dwordx4 v[62:65], v[18:19], off offset:1920
	global_load_dwordx4 v[238:241], v[22:23], off offset:1920
	global_load_dwordx4 v[66:69], v[18:19], off offset:1984
	global_load_dwordx4 v[242:245], v[22:23], off offset:1984
	s_waitcnt vmcnt(30) lgkmcnt(7)
	v_mfma_f32_16x16x32_bf16 v[2:5], v[70:73], v[138:141], v[2:5]
	v_mfma_f32_16x16x32_bf16 v[6:9], v[102:105], v[138:141], v[6:9]
	s_waitcnt vmcnt(28) lgkmcnt(6)
	v_mfma_f32_16x16x32_bf16 v[2:5], v[74:77], v[142:145], v[2:5]
	v_mfma_f32_16x16x32_bf16 v[6:9], v[106:109], v[142:145], v[6:9]
	s_waitcnt vmcnt(26) lgkmcnt(5)
	v_mfma_f32_16x16x32_bf16 v[2:5], v[78:81], v[146:149], v[2:5]
	v_mfma_f32_16x16x32_bf16 v[6:9], v[110:113], v[146:149], v[6:9]
	s_waitcnt vmcnt(24) lgkmcnt(4)
	v_mfma_f32_16x16x32_bf16 v[2:5], v[82:85], v[150:153], v[2:5]
	v_mfma_f32_16x16x32_bf16 v[6:9], v[114:117], v[150:153], v[6:9]
	s_waitcnt vmcnt(22) lgkmcnt(3)
	v_mfma_f32_16x16x32_bf16 v[2:5], v[86:89], v[154:157], v[2:5]
	v_mfma_f32_16x16x32_bf16 v[6:9], v[118:121], v[154:157], v[6:9]
	s_waitcnt vmcnt(20) lgkmcnt(2)
	v_mfma_f32_16x16x32_bf16 v[2:5], v[90:93], v[158:161], v[2:5]
	v_mfma_f32_16x16x32_bf16 v[6:9], v[122:125], v[158:161], v[6:9]
	s_waitcnt vmcnt(18) lgkmcnt(1)
	v_mfma_f32_16x16x32_bf16 v[2:5], v[94:97], v[162:165], v[2:5]
	v_mfma_f32_16x16x32_bf16 v[6:9], v[126:129], v[162:165], v[6:9]
	s_waitcnt vmcnt(16) lgkmcnt(0)
	v_mfma_f32_16x16x32_bf16 v[2:5], v[98:101], v[166:169], v[2:5]
	v_mfma_f32_16x16x32_bf16 v[6:9], v[130:133], v[166:169], v[6:9]
	ds_read_b128 v[138:141], v136 offset:24576
	ds_read_b128 v[142:145], v136 offset:25600
	ds_read_b128 v[146:149], v136 offset:26624
	ds_read_b128 v[150:153], v136 offset:27648
	ds_read_b128 v[154:157], v136 offset:28672
	ds_read_b128 v[158:161], v136 offset:29696
	ds_read_b128 v[162:165], v136 offset:30720
	ds_read_b128 v[166:169], v136 offset:31744
	s_waitcnt vmcnt(14) lgkmcnt(7)
	v_mfma_f32_16x16x32_bf16 v[2:5], v[38:41], v[138:141], v[2:5]
	v_mfma_f32_16x16x32_bf16 v[6:9], v[214:217], v[138:141], v[6:9]
	s_waitcnt vmcnt(12) lgkmcnt(6)
	v_mfma_f32_16x16x32_bf16 v[2:5], v[42:45], v[142:145], v[2:5]
	v_mfma_f32_16x16x32_bf16 v[6:9], v[218:221], v[142:145], v[6:9]
	s_waitcnt vmcnt(10) lgkmcnt(5)
	v_mfma_f32_16x16x32_bf16 v[2:5], v[46:49], v[146:149], v[2:5]
	v_mfma_f32_16x16x32_bf16 v[6:9], v[222:225], v[146:149], v[6:9]
	s_waitcnt vmcnt(8) lgkmcnt(4)
	v_mfma_f32_16x16x32_bf16 v[2:5], v[50:53], v[150:153], v[2:5]
	v_mfma_f32_16x16x32_bf16 v[6:9], v[226:229], v[150:153], v[6:9]
	s_waitcnt vmcnt(6) lgkmcnt(3)
	v_mfma_f32_16x16x32_bf16 v[2:5], v[54:57], v[154:157], v[2:5]
	v_mfma_f32_16x16x32_bf16 v[6:9], v[230:233], v[154:157], v[6:9]
	s_waitcnt vmcnt(4) lgkmcnt(2)
	v_mfma_f32_16x16x32_bf16 v[2:5], v[58:61], v[158:161], v[2:5]
	v_mfma_f32_16x16x32_bf16 v[6:9], v[234:237], v[158:161], v[6:9]
	s_waitcnt vmcnt(2) lgkmcnt(1)
	v_mfma_f32_16x16x32_bf16 v[2:5], v[62:65], v[162:165], v[2:5]
	v_mfma_f32_16x16x32_bf16 v[6:9], v[238:241], v[162:165], v[6:9]
	s_waitcnt vmcnt(0) lgkmcnt(0)
	v_mfma_f32_16x16x32_bf16 v[2:5], v[66:69], v[166:169], v[2:5]
	v_mfma_f32_16x16x32_bf16 v[6:9], v[242:245], v[166:169], v[6:9]
	s_nop 7
	v_lshl_add_u32 v0, v11, 5, s3
	v_or_b32_e32 v0, s2, v0
	v_ashrrev_i32_e32 v11, 31, v10
	v_mad_i64_i32 v[10:11], s[0:1], v0, 36, v[10:11]
	v_readlane_b32 s0, v253, 40
	v_lshlrev_b64 v[10:11], 9, v[10:11]
	v_readlane_b32 s1, v253, 41
	v_ashrrev_i32_e32 v13, 31, v12
	v_lshlrev_b32_e32 v0, 4, v24
	v_lshl_add_u64 v[10:11], s[0:1], 0, v[10:11]
	v_lshl_add_u64 v[10:11], v[12:13], 2, v[10:11]
	v_lshl_add_u64 v[10:11], v[10:11], 0, v[0:1]
	s_mov_b64 s[34:35], 0
	global_store_dwordx4 v[10:11], v[2:5], off
	global_store_dwordx4 v[10:11], v[6:9], off offset:64
